# GLA scan: the per-block image loads (q_inter / k_state / scores / decay, each read by only the four dv-slice workgroups) marked non-temporal
# speedup vs baseline: 1.0067x; 1.0049x over previous
.LBB0_243:
	s_or_b64 exec, exec, s[10:11]
	s_add_i32 s10, 0, 0x19800
	s_cmpk_lg_i32 s26, 0x7f3
	s_cselect_b32 s11, s24, 31
	s_add_i32 s28, s11, s6
	s_ashr_i32 s29, s28, 31
	s_lshl_b64 s[52:53], s[28:29], 15
	v_lshlrev_b32_e32 v8, 1, v108
	s_add_u32 s54, s13, s52
	v_and_b32_e32 v8, 0x7e, v8
	v_ashrrev_i32_e32 v9, 2, v108
	s_addc_u32 s55, s14, s53
	s_waitcnt vmcnt(6)
	v_lshlrev_b32_e32 v0, 16, v131
	s_waitcnt vmcnt(4)
	v_lshlrev_b32_e32 v1, 16, v133
	s_waitcnt vmcnt(2)
	v_lshlrev_b32_e32 v2, 16, v135
	s_waitcnt vmcnt(0)
	v_lshlrev_b32_e32 v3, 16, v137
	v_lshrrev_b32_e32 v4, 16, v130
	v_lshrrev_b32_e32 v5, 16, v132
	v_mul_u32_u24_e32 v8, 0x90, v8
	v_and_b32_e32 v9, -16, v9
	v_lshlrev_b32_e32 v208, 1, v108
	v_and_b32_e32 v208, 14, v208
	v_add_u32_e32 v208, 4, v208
	v_lshlrev_b32_e32 v208, 1, v208
	v_and_b32_e32 v208, 16, v208
	v_xor_b32_e32 v9, v9, v208
	s_add_u32 s52, s15, s52
	v_add_u32_e32 v12, 0x2000, v106
	v_add_u32_e32 v20, 0x4000, v106
	v_add_u32_e32 v28, 0x6000, v106
	v_and_or_b32 v0, v130, s35, v0
	v_and_or_b32 v1, v132, s35, v1
	v_and_or_b32 v2, v134, s35, v2
	v_and_or_b32 v3, v136, s35, v3
	v_and_or_b32 v4, v131, s88, v4
	v_and_or_b32 v5, v133, s88, v5
	v_lshrrev_b32_e32 v6, 16, v134
	v_lshrrev_b32_e32 v7, 16, v136
	v_add3_u32 v8, s10, v8, v9
	s_addc_u32 s53, s16, s53
	v_ashrrev_i32_e32 v13, 31, v12
	v_ashrrev_i32_e32 v21, 31, v20
	v_ashrrev_i32_e32 v29, 31, v28
	v_and_or_b32 v6, v135, s88, v6
	v_and_or_b32 v7, v137, s88, v7
	ds_write_b128 v8, v[0:3]
	ds_write_b128 v8, v[4:7] offset:144
	v_lshl_add_u64 v[4:5], s[52:53], 0, v[106:107]
	v_lshl_add_u64 v[8:9], s[54:55], 0, v[12:13]
	v_lshl_add_u64 v[12:13], s[52:53], 0, v[12:13]
	v_lshl_add_u64 v[16:17], s[54:55], 0, v[20:21]
	v_lshl_add_u64 v[20:21], s[52:53], 0, v[20:21]
	v_lshl_add_u64 v[24:25], s[54:55], 0, v[28:29]
	v_lshl_add_u64 v[28:29], s[52:53], 0, v[28:29]
	s_lshl_b64 s[52:53], s[28:29], 13
	s_add_u32 s52, s17, s52
	s_addc_u32 s53, s18, s53
	s_lshl_b64 s[28:29], s[28:29], 11
	s_add_u32 s28, s19, s28
	v_lshl_add_u64 v[0:1], s[54:55], 0, v[106:107]
	v_lshl_add_u64 v[32:33], s[52:53], 0, v[106:107]
	s_addc_u32 s29, s20, s29
	v_and_b32_e32 v106, 63, v108
	s_lshl_b32 s11, s11, 6
	s_waitcnt lgkmcnt(0)
	s_barrier
	v_lshlrev_b32_e32 v40, 4, v106
	s_sub_i32 s47, 0x7ff, s11
	global_load_dwordx4 v[0:3], v[0:1], off nt
	v_and_b32_e32 v107, -8, v64
	global_load_dwordx4 v[40:43], v40, s[28:29] nt
	s_and_b64 s[28:29], vcc, exec
	s_cselect_b32 s11, s11, s47
	s_add_i32 s11, s11, s7
	s_mul_hi_i32 s29, s11, 0xa080
	s_mul_i32 s11, s11, 0xa080
	v_lshl_or_b32 v106, v106, 1, s23
	s_add_u32 s28, s0, s11
	v_mad_u64_u32 v[108:109], s[52:53], v107, s22, v[106:107]
	s_addc_u32 s29, s2, s29
	v_ashrrev_i32_e32 v109, 31, v108
	v_lshl_add_u64 v[110:111], v[108:109], 1, s[28:29]
	v_add_u32_e32 v108, s22, v108
	v_ashrrev_i32_e32 v109, 31, v108
	global_load_dword v130, v[110:111], off
	v_lshl_add_u64 v[110:111], v[108:109], 1, s[28:29]
	v_add_u32_e32 v108, s22, v108
	v_ashrrev_i32_e32 v109, 31, v108
	global_load_dword v131, v[110:111], off
	v_lshl_add_u64 v[110:111], v[108:109], 1, s[28:29]
	v_add_u32_e32 v108, s22, v108
	v_ashrrev_i32_e32 v109, 31, v108
	global_load_dword v132, v[110:111], off
	v_lshl_add_u64 v[110:111], v[108:109], 1, s[28:29]
	v_add_u32_e32 v108, s22, v108
	v_ashrrev_i32_e32 v109, 31, v108
	global_load_dword v133, v[110:111], off
	v_lshl_add_u64 v[110:111], v[108:109], 1, s[28:29]
	v_add_u32_e32 v108, s22, v108
	v_ashrrev_i32_e32 v109, 31, v108
	v_or_b32_e32 v64, 7, v64
	global_load_dword v134, v[110:111], off
	v_lshl_add_u64 v[110:111], v[108:109], 1, s[28:29]
	v_add_u32_e32 v108, s22, v108
	v_mad_u64_u32 v[106:107], s[52:53], v64, s22, v[106:107]
	v_ashrrev_i32_e32 v109, 31, v108
	v_ashrrev_i32_e32 v107, 31, v106
	v_lshl_add_u64 v[108:109], v[108:109], 1, s[28:29]
	v_lshl_add_u64 v[106:107], v[106:107], 1, s[28:29]
	global_load_dwordx4 v[4:7], v[4:5], off nt
	s_nop 0
	global_load_dwordx4 v[8:11], v[8:9], off nt
	s_nop 0
	global_load_dwordx4 v[12:15], v[12:13], off nt
	s_nop 0
	global_load_dwordx4 v[16:19], v[16:17], off nt
	s_nop 0
	global_load_dwordx4 v[20:23], v[20:21], off nt
	s_nop 0
	global_load_dwordx4 v[24:27], v[24:25], off nt
	s_nop 0
	global_load_dwordx4 v[28:31], v[28:29], off nt
	s_nop 0
	global_load_dwordx4 v[32:35], v[32:33], off nt
	s_nop 0
	global_load_dword v135, v[110:111], off
	global_load_dword v136, v[108:109], off
	global_load_dword v137, v[106:107], off
	v_mov_b32_e32 v64, 0
	s_cmp_lg_u32 s36, -1
	v_add_u32_e32 v106, v64, v189
	v_and_b32_e32 v64, 15, v106
	v_ashrrev_i32_e32 v140, 4, v106
	v_and_b32_e32 v106, -16, v106
	v_add_u32_e32 v208, 4, v64
	v_lshlrev_b32_e32 v208, 1, v208
	v_and_b32_e32 v208, 16, v208
	v_xor_b32_e32 v208, v106, v208
	s_cselect_b32 s11, s36, 0
	s_cmp_lg_u32 s10, -1
	v_mad_u32_u24 v109, v64, s38, v208
	s_cselect_b32 s10, s10, 0
	s_cmp_lg_u32 0, -1
	v_mul_u32_u24_e32 v107, 0x210, v64
	v_lshlrev_b32_e32 v108, 3, v140
	v_add_u32_e32 v138, s11, v109
	s_cselect_b32 s11, 0, 0
	s_cmp_lg_u32 s27, -1
	v_add3_u32 v128, v107, s11, v108
	s_cselect_b32 s11, s27, 0
	v_add_u32_e32 v114, s11, v109
	s_add_i32 s11, 0, 0x22400
	v_or_b32_e32 v110, s4, v64
	s_cmp_lg_u32 s11, -1
	s_cselect_b32 s11, s11, 0
	v_mul_lo_u32 v107, v110, s38
	v_add_u32_e32 v139, s11, v106
	v_add3_u32 v115, v208, s10, v107
	ds_read_b64 v[106:107], v128 offset:0
	ds_read_b64 v[108:109], v128 offset:32
	ds_read_b64 v[110:111], v128 offset:0x2100
	ds_read_b64 v[112:113], v128 offset:0x2120
	ds_read_b64 v[116:117], v128 offset:0x4200
	ds_read_b64 v[118:119], v128 offset:0x4220
	ds_read_b64 v[120:121], v128 offset:0x6300
	ds_read_b64 v[122:123], v128 offset:0x6320
	ds_read_b64 v[124:125], v128 offset:64
	ds_read_b64 v[126:127], v128 offset:0x60
	ds_read_b64 v[142:143], v128 offset:0x2140
	ds_read_b64 v[144:145], v128 offset:0x2160
	ds_read_b64 v[154:155], v128 offset:0x4240
	ds_read_b64 v[156:157], v128 offset:0x4260
	ds_read_b64 v[158:159], v128 offset:0x6340
	ds_read_b64 v[160:161], v128 offset:0x6360
	s_waitcnt lgkmcnt(0)
	v_cvt_pk_bf16_f32 v162, v102, v103
	v_cvt_pk_bf16_f32 v163, v104, v105
	v_cvt_pk_bf16_f32 v164, v98, v99
	v_cvt_pk_bf16_f32 v165, v100, v101
	v_cvt_pk_bf16_f32 v166, v94, v95
	v_cvt_pk_bf16_f32 v167, v96, v97
	v_cvt_pk_bf16_f32 v168, v90, v91
	v_cvt_pk_bf16_f32 v169, v92, v93
	v_mfma_f32_16x16x32_bf16 v[106:109], v[106:109], v[162:165], 0
	v_cvt_pk_bf16_f32 v178, v74, v75
	v_cvt_pk_bf16_f32 v179, v76, v77
	v_cvt_pk_bf16_f32 v180, v66, v67
	v_mfma_f32_16x16x32_bf16 v[110:113], v[110:113], v[162:165], 0
	v_cvt_pk_bf16_f32 v181, v68, v69
	v_cvt_pk_bf16_f32 v192, v60, v61
	v_cvt_pk_bf16_f32 v193, v62, v63
	v_mfma_f32_16x16x32_bf16 v[116:119], v[116:119], v[162:165], 0
	v_cvt_pk_bf16_f32 v194, v56, v57
	v_cvt_pk_bf16_f32 v195, v58, v59
	v_mfma_f32_16x16x32_bf16 v[106:109], v[124:127], v[166:169], v[106:109]
	ds_read_b64 v[124:125], v128 offset:0x80
	ds_read_b64 v[126:127], v128 offset:0xa0
	v_mfma_f32_16x16x32_bf16 v[120:123], v[120:123], v[162:165], 0
	v_mfma_f32_16x16x32_bf16 v[110:113], v[142:145], v[166:169], v[110:113]
	ds_read_b64 v[142:143], v128 offset:0x2180
	ds_read_b64 v[144:145], v128 offset:0x21a0
	v_mfma_f32_16x16x32_bf16 v[116:119], v[154:157], v[166:169], v[116:119]
	ds_read_b64 v[154:155], v128 offset:0x4280
	ds_read_b64 v[156:157], v128 offset:0x42a0
	v_mfma_f32_16x16x32_bf16 v[120:123], v[158:161], v[166:169], v[120:123]
	ds_read_b64 v[158:159], v128 offset:0x6380
	ds_read_b64 v[160:161], v128 offset:0x63a0
	ds_read_b64 v[162:163], v128 offset:0xc0
	ds_read_b64 v[164:165], v128 offset:0xe0
	ds_read_b64 v[166:167], v128 offset:0x21c0
	ds_read_b64 v[168:169], v128 offset:0x21e0
	ds_read_b64 v[170:171], v128 offset:0x42c0
	ds_read_b64 v[172:173], v128 offset:0x42e0
	ds_read_b64 v[174:175], v128 offset:0x63c0
	ds_read_b64 v[176:177], v128 offset:0x63e0
	s_waitcnt lgkmcnt(0)
	v_mfma_f32_16x16x32_bf16 v[106:109], v[124:127], v[178:181], v[106:109]
	ds_read_b64 v[124:125], v128 offset:0x100
	ds_read_b64 v[126:127], v128 offset:0x120
	v_mfma_f32_16x16x32_bf16 v[110:113], v[142:145], v[178:181], v[110:113]
	ds_read_b64 v[142:143], v128 offset:0x2200
	ds_read_b64 v[144:145], v128 offset:0x2220
	v_mfma_f32_16x16x32_bf16 v[116:119], v[154:157], v[178:181], v[116:119]
	ds_read_b64 v[154:155], v128 offset:0x4300
	ds_read_b64 v[156:157], v128 offset:0x4320
	v_mfma_f32_16x16x32_bf16 v[120:123], v[158:161], v[178:181], v[120:123]
	ds_read_b64 v[158:159], v128 offset:0x6400
	ds_read_b64 v[160:161], v128 offset:0x6420
	v_cvt_pk_bf16_f32 v178, v86, v87
	v_mfma_f32_16x16x32_bf16 v[106:109], v[162:165], v[192:195], v[106:109]
	ds_read_b64 v[162:163], v128 offset:0x140
	ds_read_b64 v[164:165], v128 offset:0x160
	v_cvt_pk_bf16_f32 v179, v88, v89
	v_mfma_f32_16x16x32_bf16 v[110:113], v[166:169], v[192:195], v[110:113]
	ds_read_b64 v[166:167], v128 offset:0x2240
	ds_read_b64 v[168:169], v128 offset:0x2260
	v_cvt_pk_bf16_f32 v180, v82, v83
	v_mfma_f32_16x16x32_bf16 v[116:119], v[170:173], v[192:195], v[116:119]
	ds_read_b64 v[170:171], v128 offset:0x4340
	ds_read_b64 v[172:173], v128 offset:0x4360
	v_cvt_pk_bf16_f32 v181, v84, v85
	v_mfma_f32_16x16x32_bf16 v[120:123], v[174:177], v[192:195], v[120:123]
	ds_read_b64 v[174:175], v128 offset:0x6440
	ds_read_b64 v[176:177], v128 offset:0x6460
	s_waitcnt lgkmcnt(0)
	v_cvt_pk_bf16_f32 v192, v78, v79
	v_cvt_pk_bf16_f32 v193, v80, v81
	v_cvt_pk_bf16_f32 v194, v70, v71
	v_cvt_pk_bf16_f32 v195, v72, v73
	v_mfma_f32_16x16x32_bf16 v[106:109], v[124:127], v[178:181], v[106:109]
	ds_read_b64 v[124:125], v128 offset:0x180
	ds_read_b64 v[126:127], v128 offset:0x1a0
	v_mfma_f32_16x16x32_bf16 v[110:113], v[142:145], v[178:181], v[110:113]
	ds_read_b64 v[142:143], v128 offset:0x2280
	ds_read_b64 v[144:145], v128 offset:0x22a0
	v_mfma_f32_16x16x32_bf16 v[116:119], v[154:157], v[178:181], v[116:119]
	ds_read_b64 v[154:155], v128 offset:0x4380
	ds_read_b64 v[156:157], v128 offset:0x43a0
	v_mfma_f32_16x16x32_bf16 v[120:123], v[158:161], v[178:181], v[120:123]
	ds_read_b64 v[158:159], v128 offset:0x6480
	ds_read_b64 v[160:161], v128 offset:0x64a0
	v_cvt_pk_bf16_f32 v178, v48, v49
	v_mfma_f32_16x16x32_bf16 v[106:109], v[162:165], v[192:195], v[106:109]
	ds_read_b64 v[162:163], v128 offset:0x1c0
	ds_read_b64 v[164:165], v128 offset:0x1e0
	v_cvt_pk_bf16_f32 v179, v50, v51
	v_mfma_f32_16x16x32_bf16 v[110:113], v[166:169], v[192:195], v[110:113]
	ds_read_b64 v[166:167], v128 offset:0x22c0
	ds_read_b64 v[168:169], v128 offset:0x22e0
	v_cvt_pk_bf16_f32 v180, v44, v45
	v_mfma_f32_16x16x32_bf16 v[116:119], v[170:173], v[192:195], v[116:119]
	ds_read_b64 v[170:171], v128 offset:0x43c0
	ds_read_b64 v[172:173], v128 offset:0x43e0
	v_cvt_pk_bf16_f32 v181, v46, v47
	v_mfma_f32_16x16x32_bf16 v[120:123], v[174:177], v[192:195], v[120:123]
	ds_read_b64 v[174:175], v128 offset:0x64c0
	ds_read_b64 v[176:177], v128 offset:0x64e0
	s_waitcnt lgkmcnt(0)
	v_cvt_pk_bf16_f32 v192, v36, v37
	v_cvt_pk_bf16_f32 v193, v38, v39
	v_cvt_pk_bf16_f32 v194, v52, v53
	v_cvt_pk_bf16_f32 v195, v54, v55
	v_mfma_f32_16x16x32_bf16 v[110:113], v[142:145], v[178:181], v[110:113]
	v_mfma_f32_16x16x32_bf16 v[106:109], v[124:127], v[178:181], v[106:109]
	v_mfma_f32_16x16x32_bf16 v[142:145], v[166:169], v[192:195], v[110:113]
	ds_read_b128 v[110:113], v115 offset:0
	v_mfma_f32_16x16x32_bf16 v[124:127], v[162:165], v[192:195], v[106:109]
	ds_read_b128 v[106:109], v115 offset:64
	v_mfma_f32_16x16x32_bf16 v[116:119], v[154:157], v[178:181], v[116:119]
	ds_read_b128 v[154:157], v114 offset:0
	v_mfma_f32_16x16x32_bf16 v[120:123], v[158:161], v[178:181], v[120:123]
	ds_read_b128 v[158:161], v114 offset:64
	ds_read_b128 v[162:165], v114 offset:0x900
	ds_read_b128 v[166:169], v114 offset:0x940
	v_mfma_f32_16x16x32_bf16 v[116:119], v[170:173], v[192:195], v[116:119]
	ds_read_b128 v[170:173], v114 offset:0x1200
	v_mfma_f32_16x16x32_bf16 v[120:123], v[174:177], v[192:195], v[120:123]
	ds_read_b128 v[174:177], v114 offset:0x1240
	ds_read_b128 v[178:181], v114 offset:0x1b00
	ds_read_b128 v[192:195], v114 offset:0x1b40
	s_waitcnt lgkmcnt(0)
	s_nop 0
	v_mfma_f32_16x16x32_bf16 v[124:127], v[154:157], v[110:113], v[124:127]
	v_mfma_f32_16x16x32_bf16 v[142:145], v[162:165], v[110:113], v[142:145]
	v_mfma_f32_16x16x32_bf16 v[114:117], v[170:173], v[110:113], v[116:119]
	v_mfma_f32_16x16x32_bf16 v[154:157], v[178:181], v[110:113], v[120:123]
	v_mfma_f32_16x16x32_bf16 v[126:129], v[158:161], v[106:109], v[124:127]
	v_mfma_f32_16x16x32_bf16 v[122:125], v[166:169], v[106:109], v[142:145]
	ds_read_b128 v[142:145], v138 offset:0
	v_mfma_f32_16x16x32_bf16 v[118:121], v[174:177], v[106:109], v[114:117]
	v_mfma_f32_16x16x32_bf16 v[114:117], v[192:195], v[106:109], v[154:157]
	ds_read_b128 v[154:157], v138 offset:64
	ds_read_b128 v[158:161], v138 offset:0x900
	ds_read_b128 v[162:165], v138 offset:0x940
	ds_read_b128 v[166:169], v138 offset:0x1200
	ds_read_b128 v[170:173], v138 offset:0x1240
	ds_read_b128 v[174:177], v138 offset:0x1b00
	ds_read_b128 v[178:181], v138 offset:0x1b40
	ds_read_b128 v[192:195], v139 offset:0
	ds_read_b128 v[196:199], v139 offset:64
	ds_read_b128 v[200:203], v139 offset:0x80
	ds_read_b128 v[204:207], v139 offset:0xc0
	s_waitcnt lgkmcnt(0)
	s_nop 0
	v_mul_f32_e64 v104, v104, v194
	v_mul_f32_e64 v105, v105, v195
	v_pk_mul_f32 v[102:103], v[102:103], v[192:193]
	v_pk_mul_f32 v[100:101], v[100:101], v[198:199]
	v_pk_mul_f32 v[98:99], v[98:99], v[196:197]
	v_mfma_f32_16x16x32_bf16 v[102:105], v[142:145], v[110:113], v[102:105]
	v_mul_f32_e64 v96, v96, v202
	v_mul_f32_e64 v97, v97, v203
	v_pk_mul_f32 v[94:95], v[94:95], v[200:201]
	ds_read_b128 v[142:145], v138 offset:0x2400
	v_mfma_f32_16x16x32_bf16 v[98:101], v[158:161], v[110:113], v[98:101]
	v_mul_f32_e64 v92, v92, v206
	v_mul_f32_e64 v93, v93, v207
	v_pk_mul_f32 v[90:91], v[90:91], v[204:205]
	v_mfma_f32_16x16x32_bf16 v[94:97], v[166:169], v[110:113], v[94:97]
	v_mfma_f32_16x16x32_bf16 v[102:105], v[154:157], v[106:109], v[102:105]
	ds_read_b128 v[154:157], v138 offset:0x2440
	ds_read_b128 v[158:161], v138 offset:0x2d00
	v_mfma_f32_16x16x32_bf16 v[90:93], v[174:177], v[110:113], v[90:93]
	v_mfma_f32_16x16x32_bf16 v[98:101], v[162:165], v[106:109], v[98:101]
	ds_read_b128 v[162:165], v138 offset:0x2d40
	ds_read_b128 v[166:169], v138 offset:0x3600
	v_mfma_f32_16x16x32_bf16 v[94:97], v[170:173], v[106:109], v[94:97]
	ds_read_b128 v[170:173], v138 offset:0x3640
	ds_read_b128 v[174:177], v138 offset:0x3f00
	v_mfma_f32_16x16x32_bf16 v[90:93], v[178:181], v[106:109], v[90:93]
	ds_read_b128 v[178:181], v138 offset:0x3f40
	ds_read_b128 v[192:195], v139 offset:0x100
	ds_read_b128 v[196:199], v139 offset:0x140
	ds_read_b128 v[200:203], v139 offset:0x180
	ds_read_b128 v[204:207], v139 offset:0x1c0
	s_waitcnt lgkmcnt(0)
	s_nop 0
	v_mul_f32_e64 v76, v76, v194
	v_mul_f32_e64 v77, v77, v195
	v_pk_mul_f32 v[74:75], v[74:75], v[192:193]
	v_lshlrev_b32_e32 v64, 1, v64
	v_pk_mul_f32 v[68:69], v[68:69], v[198:199]
	v_mfma_f32_16x16x32_bf16 v[74:77], v[142:145], v[110:113], v[74:77]
	v_lshlrev_b32_e32 v142, 2, v140
	v_add_u32_e32 v144, s26, v142
	v_sub_u32_e32 v145, s25, v142
	v_lshl_add_u64 v[140:141], s[8:9], 0, v[64:65]
	v_cvt_pk_bf16_f32 v64, v126, s0
	v_subrev_u32_e32 v126, 51, v144
	v_add_u32_e32 v142, 0x7ff, v145
	v_cndmask_b32_e32 v126, v142, v126, vcc
	v_add_u32_e32 v142, s7, v126
	v_ashrrev_i32_e32 v143, 31, v142
	v_lshlrev_b64 v[142:143], 12, v[142:143]
	v_lshl_add_u64 v[142:143], v[140:141], 0, v[142:143]
	global_store_short v[142:143], v64, off
	v_cvt_pk_bf16_f32 v64, v127, s0
	v_subrev_u32_e32 v126, 50, v144
	v_add_u32_e32 v127, 0x7fe, v145
	v_cndmask_b32_e32 v126, v127, v126, vcc
	v_add_u32_e32 v126, s7, v126
	v_ashrrev_i32_e32 v127, 31, v126
	v_lshlrev_b64 v[126:127], 12, v[126:127]
	v_lshl_add_u64 v[126:127], v[140:141], 0, v[126:127]
	global_store_short v[126:127], v64, off
	v_subrev_u32_e32 v126, 49, v144
	v_add_u32_e32 v127, 0x7fd, v145
	v_cndmask_b32_e32 v126, v127, v126, vcc
	v_add_u32_e32 v126, s7, v126
	v_ashrrev_i32_e32 v127, 31, v126
	v_lshlrev_b64 v[126:127], 12, v[126:127]
	v_cvt_pk_bf16_f32 v64, v128, s0
	v_lshl_add_u64 v[126:127], v[140:141], 0, v[126:127]
	global_store_short v[126:127], v64, off
	v_subrev_u32_e32 v126, 48, v144
	v_add_u32_e32 v127, 0x7fc, v145
	v_cndmask_b32_e32 v126, v127, v126, vcc
	v_add_u32_e32 v126, s7, v126
	v_ashrrev_i32_e32 v127, 31, v126
	v_lshlrev_b64 v[126:127], 12, v[126:127]
	v_cvt_pk_bf16_f32 v64, v129, s0
	v_lshl_add_u64 v[126:127], v[140:141], 0, v[126:127]
	global_store_short v[126:127], v64, off
	v_cvt_pk_bf16_f32 v64, v122, s0
	v_subrev_u32_e32 v122, 35, v144
	v_add_u32_e32 v126, 0x7ef, v145
	v_cndmask_b32_e32 v122, v126, v122, vcc
	v_add_u32_e32 v126, s7, v122
	v_ashrrev_i32_e32 v127, 31, v126
	v_lshlrev_b64 v[126:127], 12, v[126:127]
	v_lshl_add_u64 v[126:127], v[140:141], 0, v[126:127]
	global_store_short v[126:127], v64, off
	v_cvt_pk_bf16_f32 v64, v123, s0
	v_subrev_u32_e32 v122, 34, v144
	v_add_u32_e32 v123, 0x7ee, v145
	v_cndmask_b32_e32 v122, v123, v122, vcc
	v_add_u32_e32 v122, s7, v122
	v_ashrrev_i32_e32 v123, 31, v122
	v_lshlrev_b64 v[122:123], 12, v[122:123]
	v_lshl_add_u64 v[122:123], v[140:141], 0, v[122:123]
	global_store_short v[122:123], v64, off
	v_subrev_u32_e32 v122, 33, v144
	v_add_u32_e32 v123, 0x7ed, v145
	v_cndmask_b32_e32 v122, v123, v122, vcc
	v_add_u32_e32 v122, s7, v122
	v_ashrrev_i32_e32 v123, 31, v122
	v_lshlrev_b64 v[122:123], 12, v[122:123]
	v_cvt_pk_bf16_f32 v64, v124, s0
	v_lshl_add_u64 v[122:123], v[140:141], 0, v[122:123]
	global_store_short v[122:123], v64, off
	v_subrev_u32_e32 v122, 32, v144
	v_add_u32_e32 v123, 0x7ec, v145
	v_cndmask_b32_e32 v122, v123, v122, vcc
	v_add_u32_e32 v122, s7, v122
	v_ashrrev_i32_e32 v123, 31, v122
	v_lshlrev_b64 v[122:123], 12, v[122:123]
	v_cvt_pk_bf16_f32 v64, v125, s0
	v_lshl_add_u64 v[122:123], v[140:141], 0, v[122:123]
	global_store_short v[122:123], v64, off
	v_cvt_pk_bf16_f32 v64, v118, s0
	v_subrev_u32_e32 v118, 19, v144
	v_add_u32_e32 v122, 0x7df, v145
	v_cndmask_b32_e32 v118, v122, v118, vcc
	v_add_u32_e32 v122, s7, v118
	v_ashrrev_i32_e32 v123, 31, v122
	v_lshlrev_b64 v[122:123], 12, v[122:123]
	v_lshl_add_u64 v[122:123], v[140:141], 0, v[122:123]
	global_store_short v[122:123], v64, off
	v_cvt_pk_bf16_f32 v64, v119, s0
	v_subrev_u32_e32 v118, 18, v144
	v_add_u32_e32 v119, 0x7de, v145
	v_cndmask_b32_e32 v118, v119, v118, vcc
	v_add_u32_e32 v118, s7, v118
	v_ashrrev_i32_e32 v119, 31, v118
	v_lshlrev_b64 v[118:119], 12, v[118:119]
	v_lshl_add_u64 v[118:119], v[140:141], 0, v[118:119]
	global_store_short v[118:119], v64, off
	v_subrev_u32_e32 v118, 17, v144
	v_add_u32_e32 v119, 0x7dd, v145
	v_cndmask_b32_e32 v118, v119, v118, vcc
	v_add_u32_e32 v118, s7, v118
	v_ashrrev_i32_e32 v119, 31, v118
	v_lshlrev_b64 v[118:119], 12, v[118:119]
	v_cvt_pk_bf16_f32 v64, v120, s0
	v_lshl_add_u64 v[118:119], v[140:141], 0, v[118:119]
	global_store_short v[118:119], v64, off
	v_add_u32_e32 v118, -16, v144
	v_add_u32_e32 v119, 0x7dc, v145
	v_cndmask_b32_e32 v118, v119, v118, vcc
	v_add_u32_e32 v118, s7, v118
	v_ashrrev_i32_e32 v119, 31, v118
	v_lshlrev_b64 v[118:119], 12, v[118:119]
	v_cvt_pk_bf16_f32 v64, v121, s0
	v_lshl_add_u64 v[118:119], v[140:141], 0, v[118:119]
	global_store_short v[118:119], v64, off
	v_cvt_pk_bf16_f32 v64, v114, s0
	v_add_u32_e32 v114, -3, v144
	v_add_u32_e32 v118, 0x7cf, v145
	v_cndmask_b32_e32 v114, v118, v114, vcc
	v_add_u32_e32 v118, s7, v114
	v_ashrrev_i32_e32 v119, 31, v118
	v_lshlrev_b64 v[118:119], 12, v[118:119]
	v_lshl_add_u64 v[118:119], v[140:141], 0, v[118:119]
	global_store_short v[118:119], v64, off
	v_cvt_pk_bf16_f32 v64, v115, s0
	v_add_u32_e32 v114, -2, v144
	v_add_u32_e32 v115, 0x7ce, v145
	v_cndmask_b32_e32 v114, v115, v114, vcc
	v_add_u32_e32 v114, s7, v114
	v_ashrrev_i32_e32 v115, 31, v114
	v_lshlrev_b64 v[114:115], 12, v[114:115]
	v_lshl_add_u64 v[114:115], v[140:141], 0, v[114:115]
	global_store_short v[114:115], v64, off
	v_add_u32_e32 v114, -1, v144
	v_add_u32_e32 v115, 0x7cd, v145
	v_cndmask_b32_e32 v114, v115, v114, vcc
	v_add_u32_e32 v114, s7, v114
	v_ashrrev_i32_e32 v115, 31, v114
	v_lshlrev_b64 v[114:115], 12, v[114:115]
	v_cvt_pk_bf16_f32 v64, v116, s0
	v_lshl_add_u64 v[114:115], v[140:141], 0, v[114:115]
	global_store_short v[114:115], v64, off
	v_add_u32_e32 v114, 0x7cc, v145
	v_cndmask_b32_e32 v114, v114, v144, vcc
	v_add_u32_e32 v114, s7, v114
	v_ashrrev_i32_e32 v115, 31, v114
	v_lshlrev_b64 v[114:115], 12, v[114:115]
	v_cvt_pk_bf16_f32 v64, v117, s0
	v_lshl_add_u64 v[114:115], v[140:141], 0, v[114:115]
	global_store_short v[114:115], v64, off
	ds_read_b128 v[114:117], v138 offset:0x4800
	ds_read_b128 v[118:121], v138 offset:0x4840
	ds_read_b128 v[122:125], v138 offset:0x5100
	v_pk_mul_f32 v[66:67], v[66:67], v[196:197]
	ds_read_b128 v[126:129], v138 offset:0x5140
	ds_read_b128 v[140:143], v138 offset:0x5a00
	v_pk_mul_f32 v[62:63], v[62:63], v[202:203]
	v_pk_mul_f32 v[60:61], v[60:61], v[200:201]
	v_mfma_f32_16x16x32_bf16 v[66:69], v[158:161], v[110:113], v[66:69]
	ds_read_b128 v[144:147], v138 offset:0x5a40
	v_mul_f32_e64 v58, v58, v206
	v_mul_f32_e64 v59, v59, v207
	v_pk_mul_f32 v[56:57], v[56:57], v[204:205]
	v_mfma_f32_16x16x32_bf16 v[60:63], v[166:169], v[110:113], v[60:63]
	v_mfma_f32_16x16x32_bf16 v[74:77], v[154:157], v[106:109], v[74:77]
	ds_read_b128 v[154:157], v138 offset:0x6300
	ds_read_b128 v[158:161], v138 offset:0x6340
	v_mfma_f32_16x16x32_bf16 v[56:59], v[174:177], v[110:113], v[56:59]
	v_mfma_f32_16x16x32_bf16 v[66:69], v[162:165], v[106:109], v[66:69]
	ds_read_b128 v[162:165], v139 offset:0x200
	ds_read_b128 v[166:169], v139 offset:0x240
	v_mfma_f32_16x16x32_bf16 v[60:63], v[170:173], v[106:109], v[60:63]
	ds_read_b128 v[170:173], v139 offset:0x280
	ds_read_b128 v[174:177], v139 offset:0x2c0
	s_waitcnt lgkmcnt(0)
	v_mfma_f32_16x16x32_bf16 v[56:59], v[178:181], v[106:109], v[56:59]
	v_mul_f32_e64 v88, v88, v164
	v_mul_f32_e64 v89, v89, v165
	v_pk_mul_f32 v[86:87], v[86:87], v[162:163]
	v_pk_mul_f32 v[84:85], v[84:85], v[168:169]
	v_pk_mul_f32 v[82:83], v[82:83], v[166:167]
	v_mfma_f32_16x16x32_bf16 v[86:89], v[114:117], v[110:113], v[86:89]
	v_mul_f32_e64 v80, v80, v172
	v_mul_f32_e64 v81, v81, v173
	v_pk_mul_f32 v[78:79], v[78:79], v[170:171]
	ds_read_b128 v[114:117], v138 offset:0x6c00
	v_mfma_f32_16x16x32_bf16 v[82:85], v[122:125], v[110:113], v[82:85]
	v_mul_f32_e64 v72, v72, v176
	v_mul_f32_e64 v73, v73, v177
	v_pk_mul_f32 v[70:71], v[70:71], v[174:175]
	v_mfma_f32_16x16x32_bf16 v[78:81], v[140:143], v[110:113], v[78:81]
	v_mfma_f32_16x16x32_bf16 v[86:89], v[118:121], v[106:109], v[86:89]
	ds_read_b128 v[118:121], v138 offset:0x6c40
	ds_read_b128 v[122:125], v138 offset:0x7500
	v_mfma_f32_16x16x32_bf16 v[70:73], v[154:157], v[110:113], v[70:73]
	v_mfma_f32_16x16x32_bf16 v[82:85], v[126:129], v[106:109], v[82:85]
	ds_read_b128 v[126:129], v138 offset:0x7540
	ds_read_b128 v[140:143], v138 offset:0x7e00
	v_mfma_f32_16x16x32_bf16 v[78:81], v[144:147], v[106:109], v[78:81]
	ds_read_b128 v[144:147], v138 offset:0x7e40
	ds_read_b128 v[154:157], v138 offset:0x8700
	v_mfma_f32_16x16x32_bf16 v[70:73], v[158:161], v[106:109], v[70:73]
	ds_read_b128 v[158:161], v138 offset:0x8740
	ds_read_b128 v[162:165], v139 offset:0x300
	ds_read_b128 v[166:169], v139 offset:0x340
	ds_read_b128 v[170:173], v139 offset:0x380
	ds_read_b128 v[174:177], v139 offset:0x3c0
	s_waitcnt lgkmcnt(0)
	s_nop 0
	v_mul_f32_e64 v50, v50, v164
	v_mul_f32_e64 v51, v51, v165
	v_pk_mul_f32 v[48:49], v[48:49], v[162:163]
	v_pk_mul_f32 v[46:47], v[46:47], v[168:169]
	v_pk_mul_f32 v[44:45], v[44:45], v[166:167]
	v_pk_mul_f32 v[38:39], v[38:39], v[172:173]
	v_pk_mul_f32 v[36:37], v[36:37], v[170:171]
	v_pk_mul_f32 v[54:55], v[54:55], v[176:177]
	v_pk_mul_f32 v[52:53], v[52:53], v[174:175]
	v_mfma_f32_16x16x32_bf16 v[48:51], v[114:117], v[110:113], v[48:51]
	s_add_i32 s26, s26, 64
	s_sub_i32 s25, s25, 64
	s_add_i32 s24, s24, 1
	v_mfma_f32_16x16x32_bf16 v[44:47], v[122:125], v[110:113], v[44:47]
	s_cmpk_lg_i32 s26, 0x833
	v_mfma_f32_16x16x32_bf16 v[36:39], v[140:143], v[110:113], v[36:39]
	v_mfma_f32_16x16x32_bf16 v[52:55], v[154:157], v[110:113], v[52:55]
	v_mfma_f32_16x16x32_bf16 v[48:51], v[118:121], v[106:109], v[48:51]
	v_mfma_f32_16x16x32_bf16 v[44:47], v[126:129], v[106:109], v[44:47]
	v_mfma_f32_16x16x32_bf16 v[36:39], v[144:147], v[106:109], v[36:39]
	v_mfma_f32_16x16x32_bf16 v[52:55], v[158:161], v[106:109], v[52:55]
	s_cbranch_scc0 .LBB0_241
